# MLP1 epilogue regenerated with 16-byte slab-row stores (relu^2 + pack, lane-pair exchange via v_permlane16_swap), on top of v73
# speedup vs baseline: 1.0396x; 1.0110x over previous
.Lpfa_skip_m1:
	s_mov_b32 s99, 1
	v_and_b32_e32 v70, 0xc0, v203
	v_or_b32_e32 v70, s43, v70
	v_lshrrev_b32_e32 v70, 5, v70
	v_mul_u32_u24_e32 v70, 0x9000, v70
	v_or_b32_e32 v71, s34, v238
	v_add3_u32 v70, v71, v239, v70
	v_lshlrev_b32_e32 v70, 6, v70
	v_lshlrev_b32_e32 v71, 3, v201
	v_and_b32_e32 v72, 1, v201
	v_mul_u32_u24_e32 v72, 24, v72
	v_add3_u32 v70, v70, v71, v72
	v_mov_b32_e32 v71, v17
	s_mov_b64 s[40:41], 0x1000
	v_lshl_add_u64 v[86:87], s[30:31], 0, v[70:71]
	v_lshl_add_u64 v[88:89], v[86:87], 0, s[40:41]
	s_mov_b64 s[40:41], 0x240000
	v_lshl_add_u64 v[118:119], v[86:87], 0, s[40:41]
	v_lshl_add_u64 v[120:121], v[88:89], 0, s[40:41]
	v_max_f32_e32 v78, 0, v158
	v_max_f32_e32 v79, 0, v159
	v_max_f32_e32 v80, 0, v160
	v_max_f32_e32 v81, 0, v161
	v_pk_mul_f32 v[78:79], v[78:79], v[78:79]
	v_pk_mul_f32 v[80:81], v[80:81], v[80:81]
	v_cvt_pk_bf16_f32 v162, v78, v79
	v_cvt_pk_bf16_f32 v163, v80, v81
	v_max_f32_e32 v82, 0, v154
	v_max_f32_e32 v83, 0, v155
	v_max_f32_e32 v84, 0, v156
	v_max_f32_e32 v85, 0, v157
	v_pk_mul_f32 v[82:83], v[82:83], v[82:83]
	v_pk_mul_f32 v[84:85], v[84:85], v[84:85]
	v_cvt_pk_bf16_f32 v164, v82, v83
	v_cvt_pk_bf16_f32 v165, v84, v85
	v_max_f32_e32 v78, 0, v150
	v_max_f32_e32 v79, 0, v151
	v_max_f32_e32 v80, 0, v152
	v_max_f32_e32 v81, 0, v153
	v_pk_mul_f32 v[78:79], v[78:79], v[78:79]
	v_pk_mul_f32 v[80:81], v[80:81], v[80:81]
	v_cvt_pk_bf16_f32 v166, v78, v79
	v_cvt_pk_bf16_f32 v167, v80, v81
	v_max_f32_e32 v82, 0, v146
	v_max_f32_e32 v83, 0, v147
	v_max_f32_e32 v84, 0, v148
	v_max_f32_e32 v85, 0, v149
	v_pk_mul_f32 v[82:83], v[82:83], v[82:83]
	v_pk_mul_f32 v[84:85], v[84:85], v[84:85]
	v_cvt_pk_bf16_f32 v168, v82, v83
	v_cvt_pk_bf16_f32 v169, v84, v85
	s_nop 1
	v_permlane16_swap_b32 v162, v164
	v_permlane16_swap_b32 v163, v165
	v_permlane16_swap_b32 v166, v168
	v_permlane16_swap_b32 v167, v169
	s_nop 1
	global_store_dwordx4 v[86:87], v[162:165], off
	global_store_dwordx4 v[118:119], v[166:169], off
	v_max_f32_e32 v78, 0, v142
	v_max_f32_e32 v79, 0, v143
	v_max_f32_e32 v80, 0, v144
	v_max_f32_e32 v81, 0, v145
	v_pk_mul_f32 v[78:79], v[78:79], v[78:79]
	v_pk_mul_f32 v[80:81], v[80:81], v[80:81]
	v_cvt_pk_bf16_f32 v170, v78, v79
	v_cvt_pk_bf16_f32 v171, v80, v81
	v_max_f32_e32 v82, 0, v138
	v_max_f32_e32 v83, 0, v139
	v_max_f32_e32 v84, 0, v140
	v_max_f32_e32 v85, 0, v141
	v_pk_mul_f32 v[82:83], v[82:83], v[82:83]
	v_pk_mul_f32 v[84:85], v[84:85], v[84:85]
	v_cvt_pk_bf16_f32 v172, v82, v83
	v_cvt_pk_bf16_f32 v173, v84, v85
	v_max_f32_e32 v78, 0, v134
	v_max_f32_e32 v79, 0, v135
	v_max_f32_e32 v80, 0, v136
	v_max_f32_e32 v81, 0, v137
	v_pk_mul_f32 v[78:79], v[78:79], v[78:79]
	v_pk_mul_f32 v[80:81], v[80:81], v[80:81]
	v_cvt_pk_bf16_f32 v174, v78, v79
	v_cvt_pk_bf16_f32 v175, v80, v81
	v_max_f32_e32 v82, 0, v114
	v_max_f32_e32 v83, 0, v115
	v_max_f32_e32 v84, 0, v116
	v_max_f32_e32 v85, 0, v117
	v_pk_mul_f32 v[82:83], v[82:83], v[82:83]
	v_pk_mul_f32 v[84:85], v[84:85], v[84:85]
	v_cvt_pk_bf16_f32 v176, v82, v83
	v_cvt_pk_bf16_f32 v177, v84, v85
	s_nop 1
	v_permlane16_swap_b32 v170, v172
	v_permlane16_swap_b32 v171, v173
	v_permlane16_swap_b32 v174, v176
	v_permlane16_swap_b32 v175, v177
	s_nop 1
	global_store_dwordx4 v[86:87], v[170:173], off offset:1024
	global_store_dwordx4 v[118:119], v[174:177], off offset:1024
	v_max_f32_e32 v78, 0, v110
	v_max_f32_e32 v79, 0, v111
	v_max_f32_e32 v80, 0, v112
	v_max_f32_e32 v81, 0, v113
	v_pk_mul_f32 v[78:79], v[78:79], v[78:79]
	v_pk_mul_f32 v[80:81], v[80:81], v[80:81]
	v_cvt_pk_bf16_f32 v162, v78, v79
	v_cvt_pk_bf16_f32 v163, v80, v81
	v_max_f32_e32 v82, 0, v106
	v_max_f32_e32 v83, 0, v107
	v_max_f32_e32 v84, 0, v108
	v_max_f32_e32 v85, 0, v109
	v_pk_mul_f32 v[82:83], v[82:83], v[82:83]
	v_pk_mul_f32 v[84:85], v[84:85], v[84:85]
	v_cvt_pk_bf16_f32 v164, v82, v83
	v_cvt_pk_bf16_f32 v165, v84, v85
	v_max_f32_e32 v78, 0, v102
	v_max_f32_e32 v79, 0, v103
	v_max_f32_e32 v80, 0, v104
	v_max_f32_e32 v81, 0, v105
	v_pk_mul_f32 v[78:79], v[78:79], v[78:79]
	v_pk_mul_f32 v[80:81], v[80:81], v[80:81]
	v_cvt_pk_bf16_f32 v166, v78, v79
	v_cvt_pk_bf16_f32 v167, v80, v81
	v_max_f32_e32 v82, 0, v98
	v_max_f32_e32 v83, 0, v99
	v_max_f32_e32 v84, 0, v100
	v_max_f32_e32 v85, 0, v101
	v_pk_mul_f32 v[82:83], v[82:83], v[82:83]
	v_pk_mul_f32 v[84:85], v[84:85], v[84:85]
	v_cvt_pk_bf16_f32 v168, v82, v83
	v_cvt_pk_bf16_f32 v169, v84, v85
	s_nop 1
	v_permlane16_swap_b32 v162, v164
	v_permlane16_swap_b32 v163, v165
	v_permlane16_swap_b32 v166, v168
	v_permlane16_swap_b32 v167, v169
	s_nop 1
	global_store_dwordx4 v[86:87], v[162:165], off offset:2048
	global_store_dwordx4 v[118:119], v[166:169], off offset:2048
	v_max_f32_e32 v78, 0, v94
	v_max_f32_e32 v79, 0, v95
	v_max_f32_e32 v80, 0, v96
	v_max_f32_e32 v81, 0, v97
	v_pk_mul_f32 v[78:79], v[78:79], v[78:79]
	v_pk_mul_f32 v[80:81], v[80:81], v[80:81]
	v_cvt_pk_bf16_f32 v170, v78, v79
	v_cvt_pk_bf16_f32 v171, v80, v81
	v_max_f32_e32 v82, 0, v90
	v_max_f32_e32 v83, 0, v91
	v_max_f32_e32 v84, 0, v92
	v_max_f32_e32 v85, 0, v93
	v_pk_mul_f32 v[82:83], v[82:83], v[82:83]
	v_pk_mul_f32 v[84:85], v[84:85], v[84:85]
	v_cvt_pk_bf16_f32 v172, v82, v83
	v_cvt_pk_bf16_f32 v173, v84, v85
	v_max_f32_e32 v78, 0, v74
	v_max_f32_e32 v79, 0, v75
	v_max_f32_e32 v80, 0, v76
	v_max_f32_e32 v81, 0, v77
	v_pk_mul_f32 v[78:79], v[78:79], v[78:79]
	v_pk_mul_f32 v[80:81], v[80:81], v[80:81]
	v_cvt_pk_bf16_f32 v174, v78, v79
	v_cvt_pk_bf16_f32 v175, v80, v81
	v_max_f32_e32 v82, 0, v66
	v_max_f32_e32 v83, 0, v67
	v_max_f32_e32 v84, 0, v68
	v_max_f32_e32 v85, 0, v69
	v_pk_mul_f32 v[82:83], v[82:83], v[82:83]
	v_pk_mul_f32 v[84:85], v[84:85], v[84:85]
	v_cvt_pk_bf16_f32 v176, v82, v83
	v_cvt_pk_bf16_f32 v177, v84, v85
	s_nop 1
	v_permlane16_swap_b32 v170, v172
	v_permlane16_swap_b32 v171, v173
	v_permlane16_swap_b32 v174, v176
	v_permlane16_swap_b32 v175, v177
	s_nop 1
	global_store_dwordx4 v[86:87], v[170:173], off offset:3072
	global_store_dwordx4 v[118:119], v[174:177], off offset:3072
	v_max_f32_e32 v78, 0, v62
	v_max_f32_e32 v79, 0, v63
	v_max_f32_e32 v80, 0, v64
	v_max_f32_e32 v81, 0, v65
	v_pk_mul_f32 v[78:79], v[78:79], v[78:79]
	v_pk_mul_f32 v[80:81], v[80:81], v[80:81]
	v_cvt_pk_bf16_f32 v162, v78, v79
	v_cvt_pk_bf16_f32 v163, v80, v81
	v_max_f32_e32 v82, 0, v58
	v_max_f32_e32 v83, 0, v59
	v_max_f32_e32 v84, 0, v60
	v_max_f32_e32 v85, 0, v61
	v_pk_mul_f32 v[82:83], v[82:83], v[82:83]
	v_pk_mul_f32 v[84:85], v[84:85], v[84:85]
	v_cvt_pk_bf16_f32 v164, v82, v83
	v_cvt_pk_bf16_f32 v165, v84, v85
	v_max_f32_e32 v78, 0, v54
	v_max_f32_e32 v79, 0, v55
	v_max_f32_e32 v80, 0, v56
	v_max_f32_e32 v81, 0, v57
	v_pk_mul_f32 v[78:79], v[78:79], v[78:79]
	v_pk_mul_f32 v[80:81], v[80:81], v[80:81]
	v_cvt_pk_bf16_f32 v166, v78, v79
	v_cvt_pk_bf16_f32 v167, v80, v81
	v_max_f32_e32 v82, 0, v50
	v_max_f32_e32 v83, 0, v51
	v_max_f32_e32 v84, 0, v52
	v_max_f32_e32 v85, 0, v53
	v_pk_mul_f32 v[82:83], v[82:83], v[82:83]
	v_pk_mul_f32 v[84:85], v[84:85], v[84:85]
	v_cvt_pk_bf16_f32 v168, v82, v83
	v_cvt_pk_bf16_f32 v169, v84, v85
	s_nop 1
	v_permlane16_swap_b32 v162, v164
	v_permlane16_swap_b32 v163, v165
	v_permlane16_swap_b32 v166, v168
	v_permlane16_swap_b32 v167, v169
	s_nop 1
	global_store_dwordx4 v[88:89], v[162:165], off
	global_store_dwordx4 v[120:121], v[166:169], off
	v_max_f32_e32 v78, 0, v46
	v_max_f32_e32 v79, 0, v47
	v_max_f32_e32 v80, 0, v48
	v_max_f32_e32 v81, 0, v49
	v_pk_mul_f32 v[78:79], v[78:79], v[78:79]
	v_pk_mul_f32 v[80:81], v[80:81], v[80:81]
	v_cvt_pk_bf16_f32 v170, v78, v79
	v_cvt_pk_bf16_f32 v171, v80, v81
	v_max_f32_e32 v82, 0, v42
	v_max_f32_e32 v83, 0, v43
	v_max_f32_e32 v84, 0, v44
	v_max_f32_e32 v85, 0, v45
	v_pk_mul_f32 v[82:83], v[82:83], v[82:83]
	v_pk_mul_f32 v[84:85], v[84:85], v[84:85]
	v_cvt_pk_bf16_f32 v172, v82, v83
	v_cvt_pk_bf16_f32 v173, v84, v85
	v_max_f32_e32 v78, 0, v38
	v_max_f32_e32 v79, 0, v39
	v_max_f32_e32 v80, 0, v40
	v_max_f32_e32 v81, 0, v41
	v_pk_mul_f32 v[78:79], v[78:79], v[78:79]
	v_pk_mul_f32 v[80:81], v[80:81], v[80:81]
	v_cvt_pk_bf16_f32 v174, v78, v79
	v_cvt_pk_bf16_f32 v175, v80, v81
	v_max_f32_e32 v82, 0, v34
	v_max_f32_e32 v83, 0, v35
	v_max_f32_e32 v84, 0, v36
	v_max_f32_e32 v85, 0, v37
	v_pk_mul_f32 v[82:83], v[82:83], v[82:83]
	v_pk_mul_f32 v[84:85], v[84:85], v[84:85]
	v_cvt_pk_bf16_f32 v176, v82, v83
	v_cvt_pk_bf16_f32 v177, v84, v85
	s_nop 1
	v_permlane16_swap_b32 v170, v172
	v_permlane16_swap_b32 v171, v173
	v_permlane16_swap_b32 v174, v176
	v_permlane16_swap_b32 v175, v177
	s_nop 1
	global_store_dwordx4 v[88:89], v[170:173], off offset:1024
	global_store_dwordx4 v[120:121], v[174:177], off offset:1024
	v_max_f32_e32 v78, 0, v30
	v_max_f32_e32 v79, 0, v31
	v_max_f32_e32 v80, 0, v32
	v_max_f32_e32 v81, 0, v33
	v_pk_mul_f32 v[78:79], v[78:79], v[78:79]
	v_pk_mul_f32 v[80:81], v[80:81], v[80:81]
	v_cvt_pk_bf16_f32 v162, v78, v79
	v_cvt_pk_bf16_f32 v163, v80, v81
	v_max_f32_e32 v82, 0, v18
	v_max_f32_e32 v83, 0, v19
	v_max_f32_e32 v84, 0, v20
	v_max_f32_e32 v85, 0, v21
	v_pk_mul_f32 v[82:83], v[82:83], v[82:83]
	v_pk_mul_f32 v[84:85], v[84:85], v[84:85]
	v_cvt_pk_bf16_f32 v164, v82, v83
	v_cvt_pk_bf16_f32 v165, v84, v85
	v_max_f32_e32 v78, 0, v12
	v_max_f32_e32 v79, 0, v13
	v_max_f32_e32 v80, 0, v14
	v_max_f32_e32 v81, 0, v15
	v_pk_mul_f32 v[78:79], v[78:79], v[78:79]
	v_pk_mul_f32 v[80:81], v[80:81], v[80:81]
	v_cvt_pk_bf16_f32 v166, v78, v79
	v_cvt_pk_bf16_f32 v167, v80, v81
	v_max_f32_e32 v82, 0, v4
	v_max_f32_e32 v83, 0, v5
	v_max_f32_e32 v84, 0, v6
	v_max_f32_e32 v85, 0, v7
	v_pk_mul_f32 v[82:83], v[82:83], v[82:83]
	v_pk_mul_f32 v[84:85], v[84:85], v[84:85]
	v_cvt_pk_bf16_f32 v168, v82, v83
	v_cvt_pk_bf16_f32 v169, v84, v85
	s_nop 1
	v_permlane16_swap_b32 v162, v164
	v_permlane16_swap_b32 v163, v165
	v_permlane16_swap_b32 v166, v168
	v_permlane16_swap_b32 v167, v169
	s_nop 1
	global_store_dwordx4 v[88:89], v[162:165], off offset:2048
	global_store_dwordx4 v[120:121], v[166:169], off offset:2048
	v_max_f32_e32 v78, 0, v0
	v_max_f32_e32 v79, 0, v1
	v_max_f32_e32 v80, 0, v2
	v_max_f32_e32 v81, 0, v3
	v_pk_mul_f32 v[78:79], v[78:79], v[78:79]
	v_pk_mul_f32 v[80:81], v[80:81], v[80:81]
	v_cvt_pk_bf16_f32 v170, v78, v79
	v_cvt_pk_bf16_f32 v171, v80, v81
	v_max_f32_e32 v82, 0, v26
	v_max_f32_e32 v83, 0, v27
	v_max_f32_e32 v84, 0, v28
	v_max_f32_e32 v85, 0, v29
	v_pk_mul_f32 v[82:83], v[82:83], v[82:83]
	v_pk_mul_f32 v[84:85], v[84:85], v[84:85]
	v_cvt_pk_bf16_f32 v172, v82, v83
	v_cvt_pk_bf16_f32 v173, v84, v85
	v_max_f32_e32 v78, 0, v22
	v_max_f32_e32 v79, 0, v23
	v_max_f32_e32 v80, 0, v24
	v_max_f32_e32 v81, 0, v25
	v_pk_mul_f32 v[78:79], v[78:79], v[78:79]
	v_pk_mul_f32 v[80:81], v[80:81], v[80:81]
	v_cvt_pk_bf16_f32 v174, v78, v79
	v_cvt_pk_bf16_f32 v175, v80, v81
	v_max_f32_e32 v82, 0, v8
	v_max_f32_e32 v83, 0, v9
	v_max_f32_e32 v84, 0, v10
	v_max_f32_e32 v85, 0, v11
	v_pk_mul_f32 v[82:83], v[82:83], v[82:83]
	v_pk_mul_f32 v[84:85], v[84:85], v[84:85]
	v_cvt_pk_bf16_f32 v176, v82, v83
	v_cvt_pk_bf16_f32 v177, v84, v85
	s_nop 1
	v_permlane16_swap_b32 v170, v172
	v_permlane16_swap_b32 v171, v173
	v_permlane16_swap_b32 v174, v176
	v_permlane16_swap_b32 v175, v177
	s_nop 1
	global_store_dwordx4 v[88:89], v[170:173], off offset:3072
	global_store_dwordx4 v[120:121], v[174:177], off offset:3072
